# topk: up to three cheap proportional threshold retries before the exact bit search
# speedup vs baseline: 1.1965x; 1.0019x over previous
; __device__ void topk_unit(const Params& p, unsigned char* smem, int unit) {
;     ...
;     for (int hf = 0; hf < 2; ++hf) {
;       const int c_ = cnt[hf][0] + cnt[hf][1] + cnt[hf][2] + cnt[hf][3];
;       const unsigned long long bm = __ballot(c_ == 15);
;       const int srcT = __ffsll((long long)bm) - 1;
;       const unsigned T0 = (unsigned)__shfl((int)mxk[hf], srcT);
.Ltk_retry:
	s_cmp_ge_u32 s10, 3
	s_cbranch_scc1 .Ltk_retry1
	s_sub_i32 s0, s0, 8
	s_sub_i32 s1, s1, 8
	s_lshl_b32 s0, s0, 18
	s_lshl_b32 s1, s1, 18
	s_add_i32 s84, s84, s0
	s_add_i32 s85, s85, s1
	s_add_i32 s10, s10, 1
	s_branch .Ltk_stepD
.Ltk_retry1:
	s_cmp_eq_u32 s10, 3
	s_cbranch_scc0 .Ltk_fine
	v_max_u32_e32 v6, v2, v3
	v_max_u32_e32 v7, v4, v5
	s_mov_b32 s84, 0
	s_mov_b32 s85, 0
	s_or_b32 s86, s84, 0x80000000
	s_or_b32 s87, s85, 0x80000000
	v_cmp_ge_u32_e64 s[68:69], v6, s86
	v_cmp_ge_u32_e64 s[70:71], v7, s87
	s_bcnt1_i32_b64 s72, s[68:69]
	s_bcnt1_i32_b64 s73, s[70:71]
	s_cmp_ge_u32 s72, 16
	s_cselect_b32 s84, s86, s84
	s_cmp_ge_u32 s73, 16
	s_cselect_b32 s85, s87, s85
	s_or_b32 s86, s84, 0x40000000
	s_or_b32 s87, s85, 0x40000000
	v_cmp_ge_u32_e64 s[68:69], v6, s86
	v_cmp_ge_u32_e64 s[70:71], v7, s87
	s_bcnt1_i32_b64 s72, s[68:69]
	s_bcnt1_i32_b64 s73, s[70:71]
	s_cmp_ge_u32 s72, 16
	s_cselect_b32 s84, s86, s84
	s_cmp_ge_u32 s73, 16
	s_cselect_b32 s85, s87, s85
	s_or_b32 s86, s84, 0x20000000
	s_or_b32 s87, s85, 0x20000000
	v_cmp_ge_u32_e64 s[68:69], v6, s86
	v_cmp_ge_u32_e64 s[70:71], v7, s87
	s_bcnt1_i32_b64 s72, s[68:69]
	s_bcnt1_i32_b64 s73, s[70:71]
	s_cmp_ge_u32 s72, 16
	s_cselect_b32 s84, s86, s84
	s_cmp_ge_u32 s73, 16
	s_cselect_b32 s85, s87, s85
	s_or_b32 s86, s84, 0x10000000
	s_or_b32 s87, s85, 0x10000000
	v_cmp_ge_u32_e64 s[68:69], v6, s86
	v_cmp_ge_u32_e64 s[70:71], v7, s87
	s_bcnt1_i32_b64 s72, s[68:69]
	s_bcnt1_i32_b64 s73, s[70:71]
	s_cmp_ge_u32 s72, 16
	s_cselect_b32 s84, s86, s84
	s_cmp_ge_u32 s73, 16
	s_cselect_b32 s85, s87, s85
	s_or_b32 s86, s84, 0x8000000
	s_or_b32 s87, s85, 0x8000000
	v_cmp_ge_u32_e64 s[68:69], v6, s86
	v_cmp_ge_u32_e64 s[70:71], v7, s87
	s_bcnt1_i32_b64 s72, s[68:69]
	s_bcnt1_i32_b64 s73, s[70:71]
	s_cmp_ge_u32 s72, 16
	s_cselect_b32 s84, s86, s84
	s_cmp_ge_u32 s73, 16
	s_cselect_b32 s85, s87, s85
	s_or_b32 s86, s84, 0x4000000
	s_or_b32 s87, s85, 0x4000000
	v_cmp_ge_u32_e64 s[68:69], v6, s86
	v_cmp_ge_u32_e64 s[70:71], v7, s87
	s_bcnt1_i32_b64 s72, s[68:69]
	s_bcnt1_i32_b64 s73, s[70:71]
	s_cmp_ge_u32 s72, 16
	s_cselect_b32 s84, s86, s84
	s_cmp_ge_u32 s73, 16
	s_cselect_b32 s85, s87, s85
	s_or_b32 s86, s84, 0x2000000
	s_or_b32 s87, s85, 0x2000000
	v_cmp_ge_u32_e64 s[68:69], v6, s86
	v_cmp_ge_u32_e64 s[70:71], v7, s87
	s_bcnt1_i32_b64 s72, s[68:69]
	s_bcnt1_i32_b64 s73, s[70:71]
	s_cmp_ge_u32 s72, 16
	s_cselect_b32 s84, s86, s84
	s_cmp_ge_u32 s73, 16
	s_cselect_b32 s85, s87, s85
	s_or_b32 s86, s84, 0x1000000
	s_or_b32 s87, s85, 0x1000000
	v_cmp_ge_u32_e64 s[68:69], v6, s86
	v_cmp_ge_u32_e64 s[70:71], v7, s87
	s_bcnt1_i32_b64 s72, s[68:69]
	s_bcnt1_i32_b64 s73, s[70:71]
	s_cmp_ge_u32 s72, 16
	s_cselect_b32 s84, s86, s84
	s_cmp_ge_u32 s73, 16
	s_cselect_b32 s85, s87, s85
	s_or_b32 s86, s84, 0x800000
	s_or_b32 s87, s85, 0x800000
	v_cmp_ge_u32_e64 s[68:69], v6, s86
	v_cmp_ge_u32_e64 s[70:71], v7, s87
	s_bcnt1_i32_b64 s72, s[68:69]
	s_bcnt1_i32_b64 s73, s[70:71]
	s_cmp_ge_u32 s72, 16
	s_cselect_b32 s84, s86, s84
	s_cmp_ge_u32 s73, 16
	s_cselect_b32 s85, s87, s85
	s_or_b32 s86, s84, 0x400000
	s_or_b32 s87, s85, 0x400000
	v_cmp_ge_u32_e64 s[68:69], v6, s86
	v_cmp_ge_u32_e64 s[70:71], v7, s87
	s_bcnt1_i32_b64 s72, s[68:69]
	s_bcnt1_i32_b64 s73, s[70:71]
	s_cmp_ge_u32 s72, 16
	s_cselect_b32 s84, s86, s84
	s_cmp_ge_u32 s73, 16
	s_cselect_b32 s85, s87, s85
	s_or_b32 s86, s84, 0x200000
	s_or_b32 s87, s85, 0x200000
	v_cmp_ge_u32_e64 s[68:69], v6, s86
	v_cmp_ge_u32_e64 s[70:71], v7, s87
	s_bcnt1_i32_b64 s72, s[68:69]
	s_bcnt1_i32_b64 s73, s[70:71]
	s_cmp_ge_u32 s72, 16
	s_cselect_b32 s84, s86, s84
	s_cmp_ge_u32 s73, 16
	s_cselect_b32 s85, s87, s85
	s_mov_b32 s10, 4
	s_branch .Ltk_stepD
; __device__ void topk_unit(const Params& p, unsigned char* smem, int unit) {
;     ...
;     for (int hf = 0; hf < 2; ++hf) {
;       const int c_ = cnt[hf][0] + cnt[hf][1] + cnt[hf][2] + cnt[hf][3];
;       const unsigned long long bm = __ballot(c_ == 15);
;       const int srcT = __ffsll((long long)bm) - 1;
;       const unsigned T0 = (unsigned)__shfl((int)mxk[hf], srcT);
.Ltk_fine:
	s_or_b32 s86, s84, 0x100000
	s_or_b32 s87, s85, 0x100000
	v_cmp_ge_u32_e64 s[68:69], v6, s86
	v_cmp_ge_u32_e64 s[70:71], v7, s87
	s_bcnt1_i32_b64 s72, s[68:69]
	s_bcnt1_i32_b64 s73, s[70:71]
	s_cmp_ge_u32 s72, 16
	s_cselect_b32 s84, s86, s84
	s_cmp_ge_u32 s73, 16
	s_cselect_b32 s85, s87, s85
	s_or_b32 s86, s84, 0x80000
	s_or_b32 s87, s85, 0x80000
	v_cmp_ge_u32_e64 s[68:69], v6, s86
	v_cmp_ge_u32_e64 s[70:71], v7, s87
	s_bcnt1_i32_b64 s72, s[68:69]
	s_bcnt1_i32_b64 s73, s[70:71]
	s_cmp_ge_u32 s72, 16
	s_cselect_b32 s84, s86, s84
	s_cmp_ge_u32 s73, 16
	s_cselect_b32 s85, s87, s85
	s_or_b32 s86, s84, 0x40000
	s_or_b32 s87, s85, 0x40000
	v_cmp_ge_u32_e64 s[68:69], v6, s86
	v_cmp_ge_u32_e64 s[70:71], v7, s87
	s_bcnt1_i32_b64 s72, s[68:69]
	s_bcnt1_i32_b64 s73, s[70:71]
	s_cmp_ge_u32 s72, 16
	s_cselect_b32 s84, s86, s84
	s_cmp_ge_u32 s73, 16
	s_cselect_b32 s85, s87, s85
	s_or_b32 s86, s84, 0x20000
	s_or_b32 s87, s85, 0x20000
	v_cmp_ge_u32_e64 s[68:69], v6, s86
	v_cmp_ge_u32_e64 s[70:71], v7, s87
	s_bcnt1_i32_b64 s72, s[68:69]
	s_bcnt1_i32_b64 s73, s[70:71]
	s_cmp_ge_u32 s72, 16
	s_cselect_b32 s84, s86, s84
	s_cmp_ge_u32 s73, 16
	s_cselect_b32 s85, s87, s85
	s_or_b32 s86, s84, 0x10000
	s_or_b32 s87, s85, 0x10000
	v_cmp_ge_u32_e64 s[68:69], v6, s86
	v_cmp_ge_u32_e64 s[70:71], v7, s87
	s_bcnt1_i32_b64 s72, s[68:69]
	s_bcnt1_i32_b64 s73, s[70:71]
	s_cmp_ge_u32 s72, 16
	s_cselect_b32 s84, s86, s84
	s_cmp_ge_u32 s73, 16
	s_cselect_b32 s85, s87, s85
	s_or_b32 s86, s84, 0x8000
	s_or_b32 s87, s85, 0x8000
	v_cmp_ge_u32_e64 s[68:69], v6, s86
	v_cmp_ge_u32_e64 s[70:71], v7, s87
	s_bcnt1_i32_b64 s72, s[68:69]
	s_bcnt1_i32_b64 s73, s[70:71]
	s_cmp_ge_u32 s72, 16
	s_cselect_b32 s84, s86, s84
	s_cmp_ge_u32 s73, 16
	s_cselect_b32 s85, s87, s85
	s_or_b32 s86, s84, 0x4000
	s_or_b32 s87, s85, 0x4000
	v_cmp_ge_u32_e64 s[68:69], v6, s86
	v_cmp_ge_u32_e64 s[70:71], v7, s87
	s_bcnt1_i32_b64 s72, s[68:69]
	s_bcnt1_i32_b64 s73, s[70:71]
	s_cmp_ge_u32 s72, 16
	s_cselect_b32 s84, s86, s84
	s_cmp_ge_u32 s73, 16
	s_cselect_b32 s85, s87, s85
	s_or_b32 s86, s84, 0x2000
	s_or_b32 s87, s85, 0x2000
	v_cmp_ge_u32_e64 s[68:69], v6, s86
	v_cmp_ge_u32_e64 s[70:71], v7, s87
	s_bcnt1_i32_b64 s72, s[68:69]
	s_bcnt1_i32_b64 s73, s[70:71]
	s_cmp_ge_u32 s72, 16
	s_cselect_b32 s84, s86, s84
	s_cmp_ge_u32 s73, 16
	s_cselect_b32 s85, s87, s85
	s_or_b32 s86, s84, 0x1000
	s_or_b32 s87, s85, 0x1000
	v_cmp_ge_u32_e64 s[68:69], v6, s86
	v_cmp_ge_u32_e64 s[70:71], v7, s87
	s_bcnt1_i32_b64 s72, s[68:69]
	s_bcnt1_i32_b64 s73, s[70:71]
	s_cmp_ge_u32 s72, 16
	s_cselect_b32 s84, s86, s84
	s_cmp_ge_u32 s73, 16
	s_cselect_b32 s85, s87, s85
	s_or_b32 s86, s84, 0x800
	s_or_b32 s87, s85, 0x800
	v_cmp_ge_u32_e64 s[68:69], v6, s86
	v_cmp_ge_u32_e64 s[70:71], v7, s87
	s_bcnt1_i32_b64 s72, s[68:69]
	s_bcnt1_i32_b64 s73, s[70:71]
	s_cmp_ge_u32 s72, 16
	s_cselect_b32 s84, s86, s84
	s_cmp_ge_u32 s73, 16
	s_cselect_b32 s85, s87, s85
	s_or_b32 s86, s84, 0x400
	s_or_b32 s87, s85, 0x400
	v_cmp_ge_u32_e64 s[68:69], v6, s86
	v_cmp_ge_u32_e64 s[70:71], v7, s87
	s_bcnt1_i32_b64 s72, s[68:69]
	s_bcnt1_i32_b64 s73, s[70:71]
	s_cmp_ge_u32 s72, 16
	s_cselect_b32 s84, s86, s84
	s_cmp_ge_u32 s73, 16
	s_cselect_b32 s85, s87, s85
	s_or_b32 s86, s84, 0x200
	s_or_b32 s87, s85, 0x200
	v_cmp_ge_u32_e64 s[68:69], v6, s86
	v_cmp_ge_u32_e64 s[70:71], v7, s87
	s_bcnt1_i32_b64 s72, s[68:69]
	s_bcnt1_i32_b64 s73, s[70:71]
	s_cmp_ge_u32 s72, 16
	s_cselect_b32 s84, s86, s84
	s_cmp_ge_u32 s73, 16
	s_cselect_b32 s85, s87, s85
	s_or_b32 s86, s84, 0x100
	s_or_b32 s87, s85, 0x100
	v_cmp_ge_u32_e64 s[68:69], v6, s86
	v_cmp_ge_u32_e64 s[70:71], v7, s87
	s_bcnt1_i32_b64 s72, s[68:69]
	s_bcnt1_i32_b64 s73, s[70:71]
	s_cmp_ge_u32 s72, 16
	s_cselect_b32 s84, s86, s84
	s_cmp_ge_u32 s73, 16
	s_cselect_b32 s85, s87, s85
	s_or_b32 s86, s84, 0x80
	s_or_b32 s87, s85, 0x80
	v_cmp_ge_u32_e64 s[68:69], v6, s86
	v_cmp_ge_u32_e64 s[70:71], v7, s87
	s_bcnt1_i32_b64 s72, s[68:69]
	s_bcnt1_i32_b64 s73, s[70:71]
	s_cmp_ge_u32 s72, 16
	s_cselect_b32 s84, s86, s84
	s_cmp_ge_u32 s73, 16
	s_cselect_b32 s85, s87, s85
	s_or_b32 s86, s84, 64
	s_or_b32 s87, s85, 64
	v_cmp_ge_u32_e64 s[68:69], v6, s86
	v_cmp_ge_u32_e64 s[70:71], v7, s87
	s_bcnt1_i32_b64 s72, s[68:69]
	s_bcnt1_i32_b64 s73, s[70:71]
	s_cmp_ge_u32 s72, 16
	s_cselect_b32 s84, s86, s84
	s_cmp_ge_u32 s73, 16
	s_cselect_b32 s85, s87, s85
	s_or_b32 s86, s84, 32
	s_or_b32 s87, s85, 32
	v_cmp_ge_u32_e64 s[68:69], v6, s86
	v_cmp_ge_u32_e64 s[70:71], v7, s87
	s_bcnt1_i32_b64 s72, s[68:69]
	s_bcnt1_i32_b64 s73, s[70:71]
	s_cmp_ge_u32 s72, 16
	s_cselect_b32 s84, s86, s84
	s_cmp_ge_u32 s73, 16
	s_cselect_b32 s85, s87, s85
	s_or_b32 s86, s84, 16
	s_or_b32 s87, s85, 16
	v_cmp_ge_u32_e64 s[68:69], v6, s86
	v_cmp_ge_u32_e64 s[70:71], v7, s87
	s_bcnt1_i32_b64 s72, s[68:69]
	s_bcnt1_i32_b64 s73, s[70:71]
	s_cmp_ge_u32 s72, 16
	s_cselect_b32 s84, s86, s84
	s_cmp_ge_u32 s73, 16
	s_cselect_b32 s85, s87, s85
	s_or_b32 s86, s84, 8
	s_or_b32 s87, s85, 8
	v_cmp_ge_u32_e64 s[68:69], v6, s86
	v_cmp_ge_u32_e64 s[70:71], v7, s87
	s_bcnt1_i32_b64 s72, s[68:69]
	s_bcnt1_i32_b64 s73, s[70:71]
	s_cmp_ge_u32 s72, 16
	s_cselect_b32 s84, s86, s84
	s_cmp_ge_u32 s73, 16
	s_cselect_b32 s85, s87, s85
	s_or_b32 s86, s84, 4
	s_or_b32 s87, s85, 4
	v_cmp_ge_u32_e64 s[68:69], v6, s86
	v_cmp_ge_u32_e64 s[70:71], v7, s87
	s_bcnt1_i32_b64 s72, s[68:69]
	s_bcnt1_i32_b64 s73, s[70:71]
	s_cmp_ge_u32 s72, 16
	s_cselect_b32 s84, s86, s84
	s_cmp_ge_u32 s73, 16
	s_cselect_b32 s85, s87, s85
	s_or_b32 s86, s84, 2
	s_or_b32 s87, s85, 2
	v_cmp_ge_u32_e64 s[68:69], v6, s86
	v_cmp_ge_u32_e64 s[70:71], v7, s87
	s_bcnt1_i32_b64 s72, s[68:69]
	s_bcnt1_i32_b64 s73, s[70:71]
	s_cmp_ge_u32 s72, 16
	s_cselect_b32 s84, s86, s84
	s_cmp_ge_u32 s73, 16
	s_cselect_b32 s85, s87, s85
	s_or_b32 s86, s84, 1
	s_or_b32 s87, s85, 1
	v_cmp_ge_u32_e64 s[68:69], v6, s86
	v_cmp_ge_u32_e64 s[70:71], v7, s87
	s_bcnt1_i32_b64 s72, s[68:69]
	s_bcnt1_i32_b64 s73, s[70:71]
	s_cmp_ge_u32 s72, 16
	s_cselect_b32 s84, s86, s84
	s_cmp_ge_u32 s73, 16
	s_cselect_b32 s85, s87, s85
	s_mov_b32 s10, 5
	s_branch .Ltk_stepD
